# pool_pre window-2 variant: its 17 serialized row loads (load, vmcnt(0), ...) are issued up front into free registers with counted waits; plus norm wait move, K-loop peel and trims
# baseline (speedup 1.0000x reference)
.LBB0_810:
	s_or_b64 exec, exec, s[4:5]
	v_lshlrev_b32_e32 v0, 1, v201
	v_lshl_add_u64 v[2:3], s[52:53], 0, v[0:1]
	v_max_i32_e32 v150, 0, v146
	v_lshlrev_b32_e32 v150, 12, v150
	v_mov_b32_e32 v151, v1
	v_lshl_add_u64 v[150:151], v[2:3], 0, v[150:151]
	global_load_dwordx2 v[150:151], v[150:151], off
	v_max_i32_e32 v152, 0, v12
	v_lshlrev_b32_e32 v152, 12, v152
	v_mov_b32_e32 v153, v1
	v_lshl_add_u64 v[152:153], v[2:3], 0, v[152:153]
	global_load_dwordx2 v[152:153], v[152:153], off
	v_add_u32_e32 v154, 1, v12
	v_max_i32_e32 v154, 0, v154
	v_lshlrev_b32_e32 v154, 12, v154
	v_mov_b32_e32 v155, v1
	v_lshl_add_u64 v[154:155], v[2:3], 0, v[154:155]
	global_load_dwordx2 v[154:155], v[154:155], off
	v_add_u32_e32 v156, 2, v12
	v_max_i32_e32 v156, 0, v156
	v_lshlrev_b32_e32 v156, 12, v156
	v_mov_b32_e32 v157, v1
	v_lshl_add_u64 v[156:157], v[2:3], 0, v[156:157]
	global_load_dwordx2 v[156:157], v[156:157], off
	v_add_u32_e32 v158, 3, v12
	v_max_i32_e32 v158, 0, v158
	v_lshlrev_b32_e32 v158, 12, v158
	v_mov_b32_e32 v159, v1
	v_lshl_add_u64 v[158:159], v[2:3], 0, v[158:159]
	global_load_dwordx2 v[158:159], v[158:159], off
	v_add_u32_e32 v160, 4, v12
	v_max_i32_e32 v160, 0, v160
	v_lshlrev_b32_e32 v160, 12, v160
	v_mov_b32_e32 v161, v1
	v_lshl_add_u64 v[160:161], v[2:3], 0, v[160:161]
	global_load_dwordx2 v[160:161], v[160:161], off
	v_add_u32_e32 v162, 5, v12
	v_max_i32_e32 v162, 0, v162
	v_lshlrev_b32_e32 v162, 12, v162
	v_mov_b32_e32 v163, v1
	v_lshl_add_u64 v[162:163], v[2:3], 0, v[162:163]
	global_load_dwordx2 v[162:163], v[162:163], off
	v_add_u32_e32 v164, 6, v12
	v_max_i32_e32 v164, 0, v164
	v_lshlrev_b32_e32 v164, 12, v164
	v_mov_b32_e32 v165, v1
	v_lshl_add_u64 v[164:165], v[2:3], 0, v[164:165]
	global_load_dwordx2 v[164:165], v[164:165], off
	v_add_u32_e32 v166, 7, v12
	v_max_i32_e32 v166, 0, v166
	v_lshlrev_b32_e32 v166, 12, v166
	v_mov_b32_e32 v167, v1
	v_lshl_add_u64 v[166:167], v[2:3], 0, v[166:167]
	global_load_dwordx2 v[166:167], v[166:167], off
	v_add_u32_e32 v168, 8, v12
	v_max_i32_e32 v168, 0, v168
	v_lshlrev_b32_e32 v168, 12, v168
	v_mov_b32_e32 v169, v1
	v_lshl_add_u64 v[168:169], v[2:3], 0, v[168:169]
	global_load_dwordx2 v[168:169], v[168:169], off
	v_add_u32_e32 v170, 9, v12
	v_max_i32_e32 v170, 0, v170
	v_lshlrev_b32_e32 v170, 12, v170
	v_mov_b32_e32 v171, v1
	v_lshl_add_u64 v[170:171], v[2:3], 0, v[170:171]
	global_load_dwordx2 v[170:171], v[170:171], off
	v_add_u32_e32 v172, 10, v12
	v_max_i32_e32 v172, 0, v172
	v_lshlrev_b32_e32 v172, 12, v172
	v_mov_b32_e32 v173, v1
	v_lshl_add_u64 v[172:173], v[2:3], 0, v[172:173]
	global_load_dwordx2 v[172:173], v[172:173], off
	v_add_u32_e32 v174, 11, v12
	v_max_i32_e32 v174, 0, v174
	v_lshlrev_b32_e32 v174, 12, v174
	v_mov_b32_e32 v175, v1
	v_lshl_add_u64 v[174:175], v[2:3], 0, v[174:175]
	global_load_dwordx2 v[174:175], v[174:175], off
	v_add_u32_e32 v176, 12, v12
	v_max_i32_e32 v176, 0, v176
	v_lshlrev_b32_e32 v176, 12, v176
	v_mov_b32_e32 v177, v1
	v_lshl_add_u64 v[176:177], v[2:3], 0, v[176:177]
	global_load_dwordx2 v[176:177], v[176:177], off
	v_add_u32_e32 v178, 13, v12
	v_max_i32_e32 v178, 0, v178
	v_lshlrev_b32_e32 v178, 12, v178
	v_mov_b32_e32 v179, v1
	v_lshl_add_u64 v[178:179], v[2:3], 0, v[178:179]
	global_load_dwordx2 v[178:179], v[178:179], off
	v_add_u32_e32 v180, 14, v12
	v_max_i32_e32 v180, 0, v180
	v_lshlrev_b32_e32 v180, 12, v180
	v_mov_b32_e32 v181, v1
	v_lshl_add_u64 v[180:181], v[2:3], 0, v[180:181]
	global_load_dwordx2 v[180:181], v[180:181], off
	v_add_u32_e32 v182, 15, v12
	v_max_i32_e32 v182, 0, v182
	v_lshlrev_b32_e32 v182, 12, v182
	v_mov_b32_e32 v183, v1
	v_lshl_add_u64 v[182:183], v[2:3], 0, v[182:183]
	global_load_dwordx2 v[182:183], v[182:183], off
	v_readlane_b32 vcc_lo, v4, 0
	v_readlane_b32 s8, v4, 1
	v_readlane_b32 s4, v4, 2
	v_readlane_b32 s14, v4, 3
	v_readlane_b32 s50, v4, 4
	v_readlane_b32 s48, v4, 5
	v_readlane_b32 s40, v4, 6
	v_readlane_b32 s34, v4, 7
	v_readlane_b32 s30, v4, 8
	v_readlane_b32 s28, v4, 9
	v_readlane_b32 s26, v4, 10
	v_readlane_b32 s38, v4, 11
	v_readlane_b32 s6, v4, 12
	v_readlane_b32 s16, v4, 13
	v_readlane_b32 s42, v4, 14
	v_readlane_b32 s36, v4, 15
	v_readlane_b32 s18, v4, 16
	s_waitcnt vmcnt(16)
	v_lshlrev_b32_e32 v130, 16, v150
	v_and_b32_e32 v131, 0xffff0000, v150
	v_lshlrev_b32_e32 v132, 16, v151
	v_and_b32_e32 v133, 0xffff0000, v151
	v_pk_mul_f32 v[92:93], vcc, v[132:133] op_sel_hi:[0,1]
	v_pk_mul_f32 v[96:97], vcc, v[130:131] op_sel_hi:[0,1]
	v_pk_fma_f32 v[130:131], vcc, v[130:131], 0 op_sel_hi:[0,1,0]
	v_pk_fma_f32 v[132:133], vcc, v[132:133], 0 op_sel_hi:[0,1,0]
	v_cmp_gt_i32_e32 vcc, v12, v211
	s_waitcnt vmcnt(15)
	v_lshlrev_b32_e32 v138, 16, v152
	v_and_b32_e32 v139, 0xffff0000, v152
	v_lshlrev_b32_e32 v140, 16, v153
	v_and_b32_e32 v141, 0xffff0000, v153
	v_pk_mul_f32 v[78:79], s[8:9], v[140:141] op_sel_hi:[0,1]
	v_pk_mul_f32 v[80:81], s[8:9], v[138:139] op_sel_hi:[0,1]
	v_pk_fma_f32 v[132:133], s[8:9], v[140:141], v[132:133] op_sel_hi:[0,1,1]
	v_pk_fma_f32 v[138:139], s[8:9], v[138:139], v[130:131] op_sel_hi:[0,1,1]
	v_lshl_add_u64 v[130:131], s[88:89], 0, v[0:1]
	v_cndmask_b32_e32 v0, v211, v146, vcc
	v_or_b32_e32 v140, 1, v12
	v_cmp_lt_i32_e32 vcc, v12, v210
	s_waitcnt vmcnt(14)
	v_lshlrev_b32_e32 v134, 16, v154
	v_and_b32_e32 v135, 0xffff0000, v154
	v_lshlrev_b32_e32 v136, 16, v155
	v_and_b32_e32 v137, 0xffff0000, v155
	v_cndmask_b32_e32 v141, v210, v140, vcc
	v_sub_u32_e32 v0, v141, v0
	v_cvt_f32_i32_e32 v0, v0
	v_pk_fma_f32 v[92:93], s[4:5], v[136:137], v[92:93] op_sel_hi:[0,1,1] neg_lo:[0,0,1] neg_hi:[0,0,1]
	v_pk_add_f32 v[92:93], v[132:133], v[92:93]
	v_cmp_lt_i32_e32 vcc, v140, v210
	v_rcp_iflag_f32_e32 v0, v0
	v_pk_mul_f32 v[64:65], s[4:5], v[136:137] op_sel_hi:[0,1]
	v_pk_fma_f32 v[96:97], s[4:5], v[134:135], v[96:97] op_sel_hi:[0,1,1] neg_lo:[0,0,1] neg_hi:[0,0,1]
	v_pk_mul_f32 v[68:69], s[4:5], v[134:135] op_sel_hi:[0,1]
	v_pk_fma_f32 v[148:149], v[0:1], v[132:133], v[78:79] op_sel_hi:[0,1,1] neg_lo:[0,0,1] neg_hi:[0,0,1]
	v_or_b32_e32 v132, 2, v12
	v_pk_fma_f32 v[146:147], v[0:1], v[138:139], v[80:81] op_sel_hi:[0,1,1] neg_lo:[0,0,1] neg_hi:[0,0,1]
	v_cndmask_b32_e32 v0, v210, v132, vcc
	v_sub_u32_e32 v0, v0, v12
	v_cvt_f32_i32_e32 v0, v0
	v_pk_mul_f32 v[148:149], v[14:15], v[148:149]
	v_pk_mul_f32 v[146:147], v[16:17], v[146:147]
	v_pk_add_f32 v[96:97], v[138:139], v[96:97]
	v_rcp_iflag_f32_e32 v0, v0
	v_cmp_lt_i32_e32 vcc, v12, v211
	v_cvt_pk_bf16_f32 v146, v146, v147
	v_cvt_pk_bf16_f32 v147, v148, v149
	v_pk_fma_f32 v[136:137], v[0:1], v[92:93], v[64:65] op_sel_hi:[0,1,1] neg_lo:[0,0,1] neg_hi:[0,0,1]
	v_lshlrev_b64 v[148:149], 12, v[12:13]
	v_pk_fma_f32 v[134:135], v[0:1], v[96:97], v[68:69] op_sel_hi:[0,1,1] neg_lo:[0,0,1] neg_hi:[0,0,1]
	v_cndmask_b32_e32 v0, v140, v211, vcc
	v_ashrrev_i32_e32 v133, 31, v132
	v_lshl_add_u64 v[148:149], v[130:131], 0, v[148:149]
	v_pk_mul_f32 v[136:137], v[14:15], v[136:137]
	v_pk_mul_f32 v[134:135], v[16:17], v[134:135]
	v_ashrrev_i32_e32 v141, 31, v140
	v_cvt_pk_bf16_f32 v134, v134, v135
	v_cvt_pk_bf16_f32 v135, v136, v137
	v_lshlrev_b64 v[136:137], 12, v[140:141]
	v_lshl_add_u64 v[136:137], v[130:131], 0, v[136:137]
	s_waitcnt vmcnt(13)
	v_lshlrev_b32_e32 v122, 16, v156
	v_and_b32_e32 v123, 0xffff0000, v156
	v_lshlrev_b32_e32 v126, 16, v157
	v_and_b32_e32 v127, 0xffff0000, v157
	v_pk_fma_f32 v[78:79], s[14:15], v[126:127], v[78:79] op_sel_hi:[0,1,1] neg_lo:[0,0,1] neg_hi:[0,0,1]
	v_pk_mul_f32 v[54:55], s[14:15], v[126:127] op_sel_hi:[0,1]
	v_pk_mul_f32 v[58:59], s[14:15], v[122:123] op_sel_hi:[0,1]
	v_pk_fma_f32 v[80:81], s[14:15], v[122:123], v[80:81] op_sel_hi:[0,1,1] neg_lo:[0,0,1] neg_hi:[0,0,1]
	v_pk_add_f32 v[78:79], v[92:93], v[78:79]
	v_or_b32_e32 v92, 3, v12
	v_cmp_lt_i32_e64 s[14:15], v132, v210
	v_pk_add_f32 v[80:81], v[96:97], v[80:81]
	v_ashrrev_i32_e32 v93, 31, v92
	v_cndmask_b32_e64 v13, v210, v92, s[14:15]
	v_sub_u32_e32 v0, v13, v0
	v_cvt_f32_i32_e32 v0, v0
	v_cmp_gt_i32_e64 s[14:15], v92, v211
	v_rcp_iflag_f32_e32 v0, v0
	s_nop 0
	v_pk_fma_f32 v[96:97], v[0:1], v[80:81], v[58:59] op_sel_hi:[0,1,1] neg_lo:[0,0,1] neg_hi:[0,0,1]
	v_pk_fma_f32 v[122:123], v[0:1], v[78:79], v[54:55] op_sel_hi:[0,1,1] neg_lo:[0,0,1] neg_hi:[0,0,1]
	v_cndmask_b32_e64 v0, v211, v132, s[14:15]
	v_cmp_lt_i32_e64 s[14:15], v92, v210
	v_pk_mul_f32 v[122:123], v[14:15], v[122:123]
	v_pk_mul_f32 v[96:97], v[16:17], v[96:97]
	s_waitcnt vmcnt(12)
	v_lshlrev_b32_e32 v114, 16, v158
	v_and_b32_e32 v115, 0xffff0000, v158
	v_lshlrev_b32_e32 v118, 16, v159
	v_and_b32_e32 v119, 0xffff0000, v159
	v_pk_fma_f32 v[64:65], s[50:51], v[118:119], v[64:65] op_sel_hi:[0,1,1] neg_lo:[0,0,1] neg_hi:[0,0,1]
	v_pk_add_f32 v[64:65], v[78:79], v[64:65]
	v_or_b32_e32 v78, 4, v12
	v_cndmask_b32_e64 v13, v210, v78, s[14:15]
	v_sub_u32_e32 v0, v13, v0
	v_cvt_f32_i32_e32 v0, v0
	v_cvt_pk_bf16_f32 v96, v96, v97
	v_cvt_pk_bf16_f32 v97, v122, v123
	v_lshlrev_b64 v[122:123], 12, v[132:133]
	v_rcp_iflag_f32_e32 v0, v0
	v_pk_mul_f32 v[46:47], s[50:51], v[118:119] op_sel_hi:[0,1]
	v_lshl_add_u64 v[122:123], v[130:131], 0, v[122:123]
	v_pk_fma_f32 v[68:69], s[50:51], v[114:115], v[68:69] op_sel_hi:[0,1,1] neg_lo:[0,0,1] neg_hi:[0,0,1]
	v_pk_mul_f32 v[50:51], s[50:51], v[114:115] op_sel_hi:[0,1]
	v_pk_add_f32 v[68:69], v[80:81], v[68:69]
	v_cmp_lt_i32_e64 s[14:15], v78, v210
	v_pk_fma_f32 v[80:81], v[0:1], v[68:69], v[50:51] op_sel_hi:[0,1,1] neg_lo:[0,0,1] neg_hi:[0,0,1]
	v_pk_mul_f32 v[80:81], v[16:17], v[80:81]
	v_ashrrev_i32_e32 v79, 31, v78
	v_cvt_pk_bf16_f32 v80, v80, v81
	s_waitcnt vmcnt(11)
	v_lshlrev_b32_e32 v110, 16, v160
	v_and_b32_e32 v111, 0xffff0000, v160
	v_lshlrev_b32_e32 v112, 16, v161
	v_and_b32_e32 v113, 0xffff0000, v161
	v_pk_fma_f32 v[54:55], s[48:49], v[112:113], v[54:55] op_sel_hi:[0,1,1] neg_lo:[0,0,1] neg_hi:[0,0,1]
	v_pk_add_f32 v[54:55], v[64:65], v[54:55]
	v_pk_fma_f32 v[58:59], s[48:49], v[110:111], v[58:59] op_sel_hi:[0,1,1] neg_lo:[0,0,1] neg_hi:[0,0,1]
	v_pk_mul_f32 v[42:43], s[48:49], v[112:113] op_sel_hi:[0,1]
	v_pk_mul_f32 v[44:45], s[48:49], v[110:111] op_sel_hi:[0,1]
	v_pk_add_f32 v[58:59], v[68:69], v[58:59]
	s_waitcnt vmcnt(10)
	v_lshlrev_b32_e32 v102, 16, v162
	v_and_b32_e32 v103, 0xffff0000, v162
	v_lshlrev_b32_e32 v104, 16, v163
	v_and_b32_e32 v105, 0xffff0000, v163
	v_pk_fma_f32 v[50:51], s[40:41], v[102:103], v[50:51] op_sel_hi:[0,1,1] neg_lo:[0,0,1] neg_hi:[0,0,1]
	v_pk_mul_f32 v[34:35], s[40:41], v[104:105] op_sel_hi:[0,1]
	v_pk_mul_f32 v[36:37], s[40:41], v[102:103] op_sel_hi:[0,1]
	v_pk_add_f32 v[50:51], v[58:59], v[50:51]
	s_waitcnt vmcnt(9)
	v_lshlrev_b32_e32 v86, 16, v164
	v_and_b32_e32 v87, 0xffff0000, v164
	v_lshlrev_b32_e32 v88, 16, v165
	v_and_b32_e32 v89, 0xffff0000, v165
	v_pk_mul_f32 v[26:27], s[34:35], v[88:89] op_sel_hi:[0,1]
	v_pk_mul_f32 v[28:29], s[34:35], v[86:87] op_sel_hi:[0,1]
	s_waitcnt vmcnt(8)
	v_lshlrev_b32_e32 v82, 16, v166
	v_and_b32_e32 v83, 0xffff0000, v166
	v_lshlrev_b32_e32 v84, 16, v167
	v_and_b32_e32 v85, 0xffff0000, v167
	v_pk_mul_f32 v[22:23], s[30:31], v[84:85] op_sel_hi:[0,1]
	v_pk_mul_f32 v[24:25], s[30:31], v[82:83] op_sel_hi:[0,1]
	s_waitcnt vmcnt(7)
	v_lshlrev_b32_e32 v74, 16, v168
	v_and_b32_e32 v75, 0xffff0000, v168
	v_lshlrev_b32_e32 v76, 16, v169
	v_and_b32_e32 v77, 0xffff0000, v169
	v_pk_mul_f32 v[18:19], s[28:29], v[76:77] op_sel_hi:[0,1]
	v_pk_mul_f32 v[20:21], s[28:29], v[74:75] op_sel_hi:[0,1]
	s_waitcnt vmcnt(5)
	v_lshlrev_b32_e32 v100, 16, v173
	v_and_b32_e32 v101, 0xffff0000, v173
	s_waitcnt vmcnt(4)
	v_lshlrev_b32_e32 v124, 16, v174
	v_and_b32_e32 v125, 0xffff0000, v174
	v_lshlrev_b32_e32 v128, 16, v175
	v_and_b32_e32 v129, 0xffff0000, v175
	v_lshlrev_b32_e32 v98, 16, v172
	v_and_b32_e32 v99, 0xffff0000, v172
	v_pk_mul_f32 v[30:31], s[38:39], v[100:101] op_sel_hi:[0,1]
	v_pk_mul_f32 v[32:33], s[38:39], v[98:99] op_sel_hi:[0,1]
	v_pk_mul_f32 v[56:57], s[6:7], v[128:129] op_sel_hi:[0,1]
	v_pk_mul_f32 v[60:61], s[6:7], v[124:125] op_sel_hi:[0,1]
	s_waitcnt vmcnt(3)
	v_lshlrev_b32_e32 v116, 16, v176
	v_and_b32_e32 v117, 0xffff0000, v176
	v_lshlrev_b32_e32 v120, 16, v177
	v_and_b32_e32 v121, 0xffff0000, v177
	v_pk_mul_f32 v[48:49], s[16:17], v[120:121] op_sel_hi:[0,1]
	v_pk_mul_f32 v[52:53], s[16:17], v[116:117] op_sel_hi:[0,1]
	v_lshlrev_b32_e32 v72, 16, v171
	global_store_dwordx2 v[148:149], v[146:147], off
	global_store_dwordx2 v[122:123], v[96:97], off
	v_pk_fma_f32 v[96:97], v[0:1], v[64:65], v[46:47] op_sel_hi:[0,1,1] neg_lo:[0,0,1] neg_hi:[0,0,1]
	v_or_b32_e32 v64, 5, v12
	v_cndmask_b32_e32 v0, v92, v211, vcc
	v_cndmask_b32_e64 v13, v210, v64, s[14:15]
	v_sub_u32_e32 v0, v13, v0
	v_cvt_f32_i32_e32 v0, v0
	v_pk_mul_f32 v[96:97], v[14:15], v[96:97]
	v_pk_fma_f32 v[46:47], s[40:41], v[104:105], v[46:47] op_sel_hi:[0,1,1] neg_lo:[0,0,1] neg_hi:[0,0,1]
	v_cvt_pk_bf16_f32 v81, v96, v97
	v_rcp_iflag_f32_e32 v0, v0
	v_lshlrev_b64 v[96:97], 12, v[92:93]
	v_lshl_add_u64 v[96:97], v[130:131], 0, v[96:97]
	v_cmp_gt_i32_e64 s[14:15], v64, v211
	global_store_dwordx2 v[96:97], v[80:81], off
	v_pk_fma_f32 v[68:69], v[0:1], v[58:59], v[44:45] op_sel_hi:[0,1,1] neg_lo:[0,0,1] neg_hi:[0,0,1]
	v_pk_fma_f32 v[80:81], v[0:1], v[54:55], v[42:43] op_sel_hi:[0,1,1] neg_lo:[0,0,1] neg_hi:[0,0,1]
	v_pk_add_f32 v[46:47], v[54:55], v[46:47]
	v_cndmask_b32_e64 v0, v211, v78, s[14:15]
	v_or_b32_e32 v54, 6, v12
	v_cmp_lt_i32_e64 s[14:15], v64, v210
	v_pk_mul_f32 v[80:81], v[14:15], v[80:81]
	v_pk_mul_f32 v[68:69], v[16:17], v[68:69]
	v_cndmask_b32_e64 v13, v210, v54, s[14:15]
	v_sub_u32_e32 v0, v13, v0
	v_cvt_f32_i32_e32 v0, v0
	v_cvt_pk_bf16_f32 v68, v68, v69
	v_cvt_pk_bf16_f32 v69, v80, v81
	v_lshlrev_b64 v[80:81], 12, v[78:79]
	v_rcp_iflag_f32_e32 v0, v0
	v_lshl_add_u64 v[80:81], v[130:131], 0, v[80:81]
	v_pk_fma_f32 v[42:43], s[34:35], v[88:89], v[42:43] op_sel_hi:[0,1,1] neg_lo:[0,0,1] neg_hi:[0,0,1]
	v_cmp_gt_i32_e64 s[14:15], v54, v211
	global_store_dwordx2 v[80:81], v[68:69], off
	v_pk_fma_f32 v[58:59], v[0:1], v[50:51], v[36:37] op_sel_hi:[0,1,1] neg_lo:[0,0,1] neg_hi:[0,0,1]
	v_pk_fma_f32 v[68:69], v[0:1], v[46:47], v[34:35] op_sel_hi:[0,1,1] neg_lo:[0,0,1] neg_hi:[0,0,1]
	v_pk_add_f32 v[42:43], v[46:47], v[42:43]
	v_cndmask_b32_e64 v0, v211, v64, s[14:15]
	v_or_b32_e32 v46, 7, v12
	v_cmp_lt_i32_e64 s[14:15], v54, v210
	v_pk_mul_f32 v[68:69], v[14:15], v[68:69]
	v_pk_mul_f32 v[58:59], v[16:17], v[58:59]
	v_cndmask_b32_e64 v13, v210, v46, s[14:15]
	v_sub_u32_e32 v0, v13, v0
	v_cvt_f32_i32_e32 v0, v0
	v_ashrrev_i32_e32 v65, 31, v64
	v_cvt_pk_bf16_f32 v58, v58, v59
	v_cvt_pk_bf16_f32 v59, v68, v69
	v_rcp_iflag_f32_e32 v0, v0
	v_lshlrev_b64 v[68:69], 12, v[64:65]
	v_pk_fma_f32 v[44:45], s[34:35], v[86:87], v[44:45] op_sel_hi:[0,1,1] neg_lo:[0,0,1] neg_hi:[0,0,1]
	v_lshl_add_u64 v[68:69], v[130:131], 0, v[68:69]
	v_pk_add_f32 v[44:45], v[50:51], v[44:45]
	v_pk_fma_f32 v[34:35], s[30:31], v[84:85], v[34:35] op_sel_hi:[0,1,1] neg_lo:[0,0,1] neg_hi:[0,0,1]
	v_cmp_gt_i32_e64 s[14:15], v46, v211
	global_store_dwordx2 v[68:69], v[58:59], off
	v_pk_fma_f32 v[50:51], v[0:1], v[44:45], v[28:29] op_sel_hi:[0,1,1] neg_lo:[0,0,1] neg_hi:[0,0,1]
	v_pk_fma_f32 v[58:59], v[0:1], v[42:43], v[26:27] op_sel_hi:[0,1,1] neg_lo:[0,0,1] neg_hi:[0,0,1]
	v_pk_add_f32 v[34:35], v[42:43], v[34:35]
	v_cndmask_b32_e64 v0, v211, v54, s[14:15]
	v_or_b32_e32 v42, 8, v12
	v_cmp_lt_i32_e64 s[14:15], v46, v210
	v_pk_mul_f32 v[58:59], v[14:15], v[58:59]
	v_pk_mul_f32 v[50:51], v[16:17], v[50:51]
	v_cndmask_b32_e64 v13, v210, v42, s[14:15]
	v_sub_u32_e32 v0, v13, v0
	v_cvt_f32_i32_e32 v0, v0
	v_ashrrev_i32_e32 v55, 31, v54
	v_cvt_pk_bf16_f32 v50, v50, v51
	v_cvt_pk_bf16_f32 v51, v58, v59
	v_rcp_iflag_f32_e32 v0, v0
	v_lshlrev_b64 v[58:59], 12, v[54:55]
	v_pk_fma_f32 v[36:37], s[30:31], v[82:83], v[36:37] op_sel_hi:[0,1,1] neg_lo:[0,0,1] neg_hi:[0,0,1]
	v_lshl_add_u64 v[58:59], v[130:131], 0, v[58:59]
	v_pk_add_f32 v[36:37], v[44:45], v[36:37]
	v_pk_fma_f32 v[26:27], s[28:29], v[76:77], v[26:27] op_sel_hi:[0,1,1] neg_lo:[0,0,1] neg_hi:[0,0,1]
	global_store_dwordx2 v[58:59], v[50:51], off
	v_pk_fma_f32 v[44:45], v[0:1], v[36:37], v[24:25] op_sel_hi:[0,1,1] neg_lo:[0,0,1] neg_hi:[0,0,1]
	v_pk_fma_f32 v[50:51], v[0:1], v[34:35], v[22:23] op_sel_hi:[0,1,1] neg_lo:[0,0,1] neg_hi:[0,0,1]
	v_pk_add_f32 v[26:27], v[34:35], v[26:27]
	v_cndmask_b32_e32 v0, v46, v211, vcc
	v_or_b32_e32 v34, 9, v12
	v_cmp_lt_i32_e32 vcc, v42, v210
	v_pk_mul_f32 v[50:51], v[14:15], v[50:51]
	v_pk_mul_f32 v[44:45], v[16:17], v[44:45]
	v_cndmask_b32_e32 v13, v210, v34, vcc
	v_sub_u32_e32 v0, v13, v0
	v_cvt_f32_i32_e32 v0, v0
	v_ashrrev_i32_e32 v47, 31, v46
	v_and_b32_e32 v73, 0xffff0000, v171
	v_cvt_pk_bf16_f32 v44, v44, v45
	v_rcp_iflag_f32_e32 v0, v0
	v_cvt_pk_bf16_f32 v45, v50, v51
	v_lshlrev_b64 v[50:51], 12, v[46:47]
	v_pk_fma_f32 v[28:29], s[28:29], v[74:75], v[28:29] op_sel_hi:[0,1,1] neg_lo:[0,0,1] neg_hi:[0,0,1]
	v_lshl_add_u64 v[50:51], v[130:131], 0, v[50:51]
	v_pk_add_f32 v[28:29], v[36:37], v[28:29]
	v_pk_fma_f32 v[22:23], s[26:27], v[72:73], v[22:23] op_sel_hi:[0,1,1] neg_lo:[0,0,1] neg_hi:[0,0,1]
	v_cmp_gt_i32_e32 vcc, v34, v211
	global_store_dwordx2 v[50:51], v[44:45], off
	v_pk_fma_f32 v[36:37], v[0:1], v[28:29], v[20:21] op_sel_hi:[0,1,1] neg_lo:[0,0,1] neg_hi:[0,0,1]
	v_pk_fma_f32 v[44:45], v[0:1], v[26:27], v[18:19] op_sel_hi:[0,1,1] neg_lo:[0,0,1] neg_hi:[0,0,1]
	v_pk_add_f32 v[22:23], v[26:27], v[22:23]
	v_cndmask_b32_e32 v0, v211, v42, vcc
	v_or_b32_e32 v26, 10, v12
	v_cmp_lt_i32_e32 vcc, v34, v210
	v_lshlrev_b32_e32 v70, 16, v170
	v_and_b32_e32 v71, 0xffff0000, v170
	v_cndmask_b32_e32 v13, v210, v26, vcc
	v_sub_u32_e32 v0, v13, v0
	v_cvt_f32_i32_e32 v0, v0
	v_pk_mul_f32 v[44:45], v[14:15], v[44:45]
	v_pk_mul_f32 v[36:37], v[16:17], v[36:37]
	v_ashrrev_i32_e32 v43, 31, v42
	v_rcp_iflag_f32_e32 v0, v0
	v_cvt_pk_bf16_f32 v36, v36, v37
	v_cvt_pk_bf16_f32 v37, v44, v45
	v_lshlrev_b64 v[44:45], 12, v[42:43]
	v_pk_fma_f32 v[24:25], s[26:27], v[70:71], v[24:25] op_sel_hi:[0,1,1] neg_lo:[0,0,1] neg_hi:[0,0,1]
	v_pk_mul_f32 v[6:7], s[26:27], v[72:73] op_sel_hi:[0,1]
	v_pk_mul_f32 v[8:9], s[26:27], v[70:71] op_sel_hi:[0,1]
	v_lshl_add_u64 v[44:45], v[130:131], 0, v[44:45]
	v_pk_add_f32 v[24:25], v[28:29], v[24:25]
	v_pk_fma_f32 v[18:19], s[38:39], v[100:101], v[18:19] op_sel_hi:[0,1,1] neg_lo:[0,0,1] neg_hi:[0,0,1]
	v_cmp_gt_i32_e32 vcc, v26, v211
	global_store_dwordx2 v[44:45], v[36:37], off
	v_pk_fma_f32 v[28:29], v[0:1], v[24:25], v[8:9] op_sel_hi:[0,1,1] neg_lo:[0,0,1] neg_hi:[0,0,1]
	v_pk_fma_f32 v[36:37], v[0:1], v[22:23], v[6:7] op_sel_hi:[0,1,1] neg_lo:[0,0,1] neg_hi:[0,0,1]
	v_pk_add_f32 v[18:19], v[22:23], v[18:19]
	v_cndmask_b32_e32 v0, v211, v34, vcc
	v_or_b32_e32 v22, 11, v12
	v_cmp_lt_i32_e32 vcc, v26, v210
	v_pk_mul_f32 v[36:37], v[14:15], v[36:37]
	v_pk_mul_f32 v[28:29], v[16:17], v[28:29]
	v_cndmask_b32_e32 v13, v210, v22, vcc
	v_sub_u32_e32 v0, v13, v0
	v_cvt_f32_i32_e32 v0, v0
	v_ashrrev_i32_e32 v35, 31, v34
	v_cvt_pk_bf16_f32 v28, v28, v29
	v_cvt_pk_bf16_f32 v29, v36, v37
	v_rcp_iflag_f32_e32 v0, v0
	v_lshlrev_b64 v[36:37], 12, v[34:35]
	v_pk_fma_f32 v[20:21], s[38:39], v[98:99], v[20:21] op_sel_hi:[0,1,1] neg_lo:[0,0,1] neg_hi:[0,0,1]
	v_lshl_add_u64 v[36:37], v[130:131], 0, v[36:37]
	v_pk_add_f32 v[20:21], v[24:25], v[20:21]
	v_pk_fma_f32 v[6:7], s[6:7], v[128:129], v[6:7] op_sel_hi:[0,1,1] neg_lo:[0,0,1] neg_hi:[0,0,1]
	v_cmp_gt_i32_e32 vcc, v22, v211
	global_store_dwordx2 v[36:37], v[28:29], off
	v_pk_fma_f32 v[24:25], v[0:1], v[20:21], v[32:33] op_sel_hi:[0,1,1] neg_lo:[0,0,1] neg_hi:[0,0,1]
	v_pk_fma_f32 v[28:29], v[0:1], v[18:19], v[30:31] op_sel_hi:[0,1,1] neg_lo:[0,0,1] neg_hi:[0,0,1]
	v_pk_add_f32 v[6:7], v[18:19], v[6:7]
	v_cndmask_b32_e32 v0, v211, v26, vcc
	v_or_b32_e32 v18, 12, v12
	v_cmp_lt_i32_e32 vcc, v22, v210
	v_pk_mul_f32 v[28:29], v[14:15], v[28:29]
	v_pk_mul_f32 v[24:25], v[16:17], v[24:25]
	v_cndmask_b32_e32 v13, v210, v18, vcc
	v_sub_u32_e32 v0, v13, v0
	v_cvt_f32_i32_e32 v0, v0
	v_ashrrev_i32_e32 v27, 31, v26
	v_cvt_pk_bf16_f32 v24, v24, v25
	v_cvt_pk_bf16_f32 v25, v28, v29
	v_rcp_iflag_f32_e32 v0, v0
	v_lshlrev_b64 v[28:29], 12, v[26:27]
	v_pk_fma_f32 v[8:9], s[6:7], v[124:125], v[8:9] op_sel_hi:[0,1,1] neg_lo:[0,0,1] neg_hi:[0,0,1]
	v_lshl_add_u64 v[28:29], v[130:131], 0, v[28:29]
	v_pk_add_f32 v[8:9], v[20:21], v[8:9]
	global_store_dwordx2 v[28:29], v[24:25], off
	v_pk_fma_f32 v[20:21], v[0:1], v[8:9], v[60:61] op_sel_hi:[0,1,1] neg_lo:[0,0,1] neg_hi:[0,0,1]
	v_pk_fma_f32 v[24:25], v[0:1], v[6:7], v[56:57] op_sel_hi:[0,1,1] neg_lo:[0,0,1] neg_hi:[0,0,1]
	v_pk_mul_f32 v[24:25], v[14:15], v[24:25]
	v_pk_mul_f32 v[20:21], v[16:17], v[20:21]
	v_ashrrev_i32_e32 v23, 31, v22
	v_cvt_pk_bf16_f32 v20, v20, v21
	v_cvt_pk_bf16_f32 v21, v24, v25
	v_lshlrev_b64 v[24:25], 12, v[22:23]
	v_lshl_add_u64 v[24:25], v[130:131], 0, v[24:25]
	global_store_dwordx2 v[24:25], v[20:21], off
	v_pk_fma_f32 v[20:21], s[16:17], v[116:117], v[32:33] op_sel_hi:[0,1,1] neg_lo:[0,0,1] neg_hi:[0,0,1]
	v_cmp_gt_i32_e32 vcc, v18, v211
	v_pk_add_f32 v[8:9], v[8:9], v[20:21]
	v_or_b32_e32 v20, 13, v12
	v_cndmask_b32_e32 v0, v211, v22, vcc
	v_cmp_lt_i32_e32 vcc, v18, v210
	v_pk_fma_f32 v[24:25], s[16:17], v[120:121], v[30:31] op_sel_hi:[0,1,1] neg_lo:[0,0,1] neg_hi:[0,0,1]
	v_pk_add_f32 v[6:7], v[6:7], v[24:25]
	v_cndmask_b32_e32 v13, v210, v20, vcc
	v_sub_u32_e32 v0, v13, v0
	v_cvt_f32_i32_e32 v0, v0
	v_ashrrev_i32_e32 v19, 31, v18
	v_cmp_gt_i32_e32 vcc, v20, v211
	s_waitcnt vmcnt(13)
	v_lshlrev_b32_e32 v106, 16, v178
	v_rcp_iflag_f32_e32 v0, v0
	v_and_b32_e32 v107, 0xffff0000, v178
	v_lshlrev_b32_e32 v108, 16, v179
	v_and_b32_e32 v109, 0xffff0000, v179
	v_pk_fma_f32 v[22:23], v[0:1], v[8:9], v[52:53] op_sel_hi:[0,1,1] neg_lo:[0,0,1] neg_hi:[0,0,1]
	v_pk_fma_f32 v[24:25], v[0:1], v[6:7], v[48:49] op_sel_hi:[0,1,1] neg_lo:[0,0,1] neg_hi:[0,0,1]
	v_pk_mul_f32 v[24:25], v[14:15], v[24:25]
	v_pk_mul_f32 v[22:23], v[16:17], v[22:23]
	v_cndmask_b32_e32 v0, v211, v18, vcc
	v_cvt_pk_bf16_f32 v22, v22, v23
	v_cvt_pk_bf16_f32 v23, v24, v25
	v_lshlrev_b64 v[24:25], 12, v[18:19]
	v_or_b32_e32 v18, 14, v12
	v_cmp_lt_i32_e32 vcc, v20, v210
	v_lshl_add_u64 v[24:25], v[130:131], 0, v[24:25]
	global_store_dwordx2 v[24:25], v[22:23], off
	v_cndmask_b32_e32 v13, v210, v18, vcc
	v_sub_u32_e32 v0, v13, v0
	v_cvt_f32_i32_e32 v0, v0
	v_pk_fma_f32 v[22:23], s[42:43], v[106:107], v[60:61] op_sel_hi:[0,1,1] neg_lo:[0,0,1] neg_hi:[0,0,1]
	v_pk_fma_f32 v[24:25], s[42:43], v[108:109], v[56:57] op_sel_hi:[0,1,1] neg_lo:[0,0,1] neg_hi:[0,0,1]
	v_pk_mul_f32 v[38:39], s[42:43], v[108:109] op_sel_hi:[0,1]
	v_rcp_iflag_f32_e32 v0, v0
	v_pk_mul_f32 v[40:41], s[42:43], v[106:107] op_sel_hi:[0,1]
	v_pk_add_f32 v[6:7], v[6:7], v[24:25]
	v_pk_add_f32 v[8:9], v[8:9], v[22:23]
	v_pk_fma_f32 v[24:25], v[0:1], v[6:7], v[38:39] op_sel_hi:[0,1,1] neg_lo:[0,0,1] neg_hi:[0,0,1]
	v_pk_fma_f32 v[22:23], v[0:1], v[8:9], v[40:41] op_sel_hi:[0,1,1] neg_lo:[0,0,1] neg_hi:[0,0,1]
	v_pk_mul_f32 v[24:25], v[14:15], v[24:25]
	v_pk_mul_f32 v[22:23], v[16:17], v[22:23]
	v_ashrrev_i32_e32 v21, 31, v20
	v_cvt_pk_bf16_f32 v22, v22, v23
	v_cvt_pk_bf16_f32 v23, v24, v25
	v_lshlrev_b64 v[24:25], 12, v[20:21]
	s_waitcnt vmcnt(13)
	v_lshlrev_b32_e32 v90, 16, v180
	v_and_b32_e32 v91, 0xffff0000, v180
	v_lshl_add_u64 v[24:25], v[130:131], 0, v[24:25]
	v_cmp_gt_i32_e32 vcc, v18, v211
	global_store_dwordx2 v[24:25], v[22:23], off
	v_pk_fma_f32 v[22:23], s[36:37], v[90:91], v[52:53] op_sel_hi:[0,1,1] neg_lo:[0,0,1] neg_hi:[0,0,1]
	v_cndmask_b32_e32 v0, v211, v20, vcc
	v_or_b32_e32 v42, 15, v212
	v_cmp_lt_i32_e32 vcc, v18, v210
	v_pk_add_f32 v[22:23], v[8:9], v[22:23]
	v_lshlrev_b32_e32 v94, 16, v181
	v_cndmask_b32_e32 v8, v210, v42, vcc
	v_sub_u32_e32 v0, v8, v0
	v_cvt_f32_i32_e32 v0, v0
	v_and_b32_e32 v95, 0xffff0000, v181
	v_pk_fma_f32 v[24:25], s[36:37], v[94:95], v[48:49] op_sel_hi:[0,1,1] neg_lo:[0,0,1] neg_hi:[0,0,1]
	v_pk_mul_f32 v[62:63], s[36:37], v[94:95] op_sel_hi:[0,1]
	v_rcp_iflag_f32_e32 v0, v0
	v_pk_mul_f32 v[66:67], s[36:37], v[90:91] op_sel_hi:[0,1]
	v_pk_add_f32 v[6:7], v[6:7], v[24:25]
	v_ashrrev_i32_e32 v19, 31, v18
	v_pk_fma_f32 v[8:9], v[0:1], v[22:23], v[66:67] op_sel_hi:[0,1,1] neg_lo:[0,0,1] neg_hi:[0,0,1]
	v_pk_fma_f32 v[20:21], v[0:1], v[6:7], v[62:63] op_sel_hi:[0,1,1] neg_lo:[0,0,1] neg_hi:[0,0,1]
	v_pk_mul_f32 v[20:21], v[14:15], v[20:21]
	v_pk_mul_f32 v[8:9], v[16:17], v[8:9]
	v_cmp_gt_i32_e32 vcc, v42, v211
	v_cvt_pk_bf16_f32 v8, v8, v9
	v_cvt_pk_bf16_f32 v9, v20, v21
	v_lshlrev_b64 v[20:21], 12, v[18:19]
	s_waitcnt vmcnt(13)
	v_lshlrev_b32_e32 v142, 16, v182
	v_and_b32_e32 v143, 0xffff0000, v182
	v_lshlrev_b32_e32 v144, 16, v183
	v_and_b32_e32 v145, 0xffff0000, v183
	v_lshl_add_u64 v[20:21], v[130:131], 0, v[20:21]
	v_cndmask_b32_e32 v0, v211, v18, vcc
	v_add_u32_e32 v12, 16, v12
	v_cmp_lt_i32_e32 vcc, v42, v210
	global_store_dwordx2 v[20:21], v[8:9], off
	v_pk_fma_f32 v[20:21], s[18:19], v[142:143], v[40:41] op_sel_hi:[0,1,1] neg_lo:[0,0,1] neg_hi:[0,0,1]
	v_pk_fma_f32 v[8:9], s[18:19], v[144:145], v[38:39] op_sel_hi:[0,1,1] neg_lo:[0,0,1] neg_hi:[0,0,1]
	v_cndmask_b32_e32 v12, v210, v12, vcc
	v_pk_mul_f32 v[4:5], s[18:19], v[144:145] op_sel_hi:[0,1]
	v_pk_mul_f32 v[2:3], s[18:19], v[142:143] op_sel_hi:[0,1]
	global_store_dwordx2 v[136:137], v[134:135], off
	v_pk_add_f32 v[8:9], v[6:7], v[8:9]
	v_pk_add_f32 v[6:7], v[22:23], v[20:21]
	v_sub_u32_e32 v0, v12, v0
